# tiles of the GLA-needed queue segment run their K-loop at priority 1 (others 0)
# speedup vs baseline: 1.0083x; 1.0083x over previous
.LBB0_346:
	s_cmpk_gt_u32 s12, 0x8f
	s_cbranch_scc1 .Lgp_lo
	s_setprio 1
	s_branch .Lgp_done

.Lgp_done:
	v_and_b32_e32 v76, 63, v0
	v_lshrrev_b32_e32 v77, 6, v0
	v_and_b32_e32 v93, 15, v0
	v_readfirstlane_b32 s9, v77
	v_lshrrev_b32_e32 v78, 3, v76
	v_and_b32_e32 v79, 7, v76
	v_lshrrev_b32_e32 v80, 1, v78
	s_and_b32 s4, s9, 1
	s_lshl_b32 s4, s4, 2
	v_or_b32_e32 v80, s4, v80
	v_xor_b32_e32 v79, v79, v80
	s_lshl_b32 s4, s9, 3
	v_add_u32_e32 v78, s4, v78
	v_lshlrev_b32_e32 v78, 11, v78
	v_lshl_add_u32 v56, v79, 4, v78
	v_add_u32_e32 v57, 0x10000, v56
	v_add_u32_e32 v58, 0x20000, v56
	v_add_u32_e32 v59, 0x30000, v56
	s_lshl_b32 s4, s22, 18
	s_add_u32 s0, s48, s4
	s_addc_u32 s1, s49, 0
	s_lshl_b32 s4, s64, 18
	s_add_u32 s2, s44, s4
	s_addc_u32 s3, s45, 0
	s_lshl_b32 s4, s9, 10
	s_add_u32 s4, s4, 16
	v_bfe_u32 v2, v0, 4, 2
	v_bfe_u32 v81, v0, 1, 3
	v_xor_b32_e32 v82, v2, v81
	v_or_b32_e32 v83, 4, v2
	v_xor_b32_e32 v83, v83, v81
	v_lshlrev_b32_e32 v82, 4, v82
	v_lshlrev_b32_e32 v83, 4, v83
	v_lshlrev_b32_e32 v84, 7, v93
	v_ashrrev_i32_e32 v92, 7, v0
	s_lshr_b32 s9, s9, 1
	s_lshl_b32 s9, s9, 13
	v_add3_u32 v64, v84, s9, 16
	v_add_u32_e32 v65, v64, v83
	v_add_u32_e32 v64, v64, v82
	v_bfe_u32 v85, v0, 6, 1
	s_lshl_b32 s9, s64, 7
	v_lshl_or_b32 v94, v85, 6, s9
	v_lshlrev_b32_e32 v85, 13, v85
	v_add3_u32 v66, v84, v85, 16
	v_add_u32_e32 v66, 0x4000, v66
	v_add_u32_e32 v67, v66, v83
	v_add_u32_e32 v66, v66, v82
	v_mov_b32_e32 v60, 0
	v_mov_b32_e32 v61, 0
	v_mov_b32_e32 v62, 0
	v_mov_b32_e32 v63, 0
	v_mov_b32_e32 v68, 0
	v_mov_b32_e32 v69, 0
	v_mov_b32_e32 v70, 0
	v_mov_b32_e32 v71, 0
	v_mov_b32_e32 v52, 0
	v_mov_b32_e32 v53, 0
	v_mov_b32_e32 v54, 0
	v_mov_b32_e32 v55, 0
	v_mov_b32_e32 v40, 0
	v_mov_b32_e32 v41, 0
	v_mov_b32_e32 v42, 0
	v_mov_b32_e32 v43, 0
	v_mov_b32_e32 v72, 0
	v_mov_b32_e32 v73, 0
	v_mov_b32_e32 v74, 0
	v_mov_b32_e32 v75, 0
	v_mov_b32_e32 v48, 0
	v_mov_b32_e32 v49, 0
	v_mov_b32_e32 v50, 0
	v_mov_b32_e32 v51, 0
	v_mov_b32_e32 v44, 0
	v_mov_b32_e32 v45, 0
	v_mov_b32_e32 v46, 0
	v_mov_b32_e32 v47, 0
	v_mov_b32_e32 v36, 0
	v_mov_b32_e32 v37, 0
	v_mov_b32_e32 v38, 0
	v_mov_b32_e32 v39, 0
	v_mov_b32_e32 v32, 0
	v_mov_b32_e32 v33, 0
	v_mov_b32_e32 v34, 0
	v_mov_b32_e32 v35, 0
	v_mov_b32_e32 v28, 0
	v_mov_b32_e32 v29, 0
	v_mov_b32_e32 v30, 0
	v_mov_b32_e32 v31, 0
	v_mov_b32_e32 v24, 0
	v_mov_b32_e32 v25, 0
	v_mov_b32_e32 v26, 0
	v_mov_b32_e32 v27, 0
	v_mov_b32_e32 v20, 0
	v_mov_b32_e32 v21, 0
	v_mov_b32_e32 v22, 0
	v_mov_b32_e32 v23, 0
	v_mov_b32_e32 v16, 0
	v_mov_b32_e32 v17, 0
	v_mov_b32_e32 v18, 0
	v_mov_b32_e32 v19, 0
	v_mov_b32_e32 v12, 0
	v_mov_b32_e32 v13, 0
	v_mov_b32_e32 v14, 0
	v_mov_b32_e32 v15, 0
	v_mov_b32_e32 v8, 0
	v_mov_b32_e32 v9, 0
	v_mov_b32_e32 v10, 0
	v_mov_b32_e32 v11, 0
	v_mov_b32_e32 v4, 0
	v_mov_b32_e32 v5, 0
	v_mov_b32_e32 v6, 0
	v_mov_b32_e32 v7, 0
	s_cmp_eq_u32 s64, 24
	s_cbranch_scc1 .Lg1_narrow
	s_add_u32 m0, s4, 0x0
	s_nop 0
	global_load_lds_dwordx4 v56, s[0:1]
	s_add_u32 m0, s4, 0x1000
	s_nop 0
	global_load_lds_dwordx4 v57, s[0:1]
	s_add_u32 m0, s4, 0x2000
	s_nop 0
	global_load_lds_dwordx4 v58, s[0:1]
	s_add_u32 m0, s4, 0x3000
	s_nop 0
	global_load_lds_dwordx4 v59, s[0:1]
	s_add_u32 m0, s4, 0x4000
	s_nop 0
	global_load_lds_dwordx4 v56, s[2:3]
	s_add_u32 m0, s4, 0x5000
	s_nop 0
	global_load_lds_dwordx4 v57, s[2:3]
	s_add_u32 m0, s4, 0x6000
	s_nop 0
	global_load_lds_dwordx4 v58, s[2:3]
	s_add_u32 m0, s4, 0x7000
	s_nop 0
	global_load_lds_dwordx4 v59, s[2:3]
	s_add_u32 s0, s0, 0x80
	s_addc_u32 s1, s1, 0
	s_add_u32 s2, s2, 0x80
	s_addc_u32 s3, s3, 0
	s_add_u32 m0, s4, 0x8000
	s_nop 0
	global_load_lds_dwordx4 v56, s[0:1]
	s_add_u32 m0, s4, 0x9000
	s_nop 0
	global_load_lds_dwordx4 v57, s[0:1]
	s_add_u32 m0, s4, 0xa000
	s_nop 0
	global_load_lds_dwordx4 v58, s[0:1]
	s_add_u32 m0, s4, 0xb000
	s_nop 0
	global_load_lds_dwordx4 v59, s[0:1]
	s_add_u32 m0, s4, 0xc000
	s_nop 0
	global_load_lds_dwordx4 v56, s[2:3]
	s_add_u32 m0, s4, 0xd000
	s_nop 0
	global_load_lds_dwordx4 v57, s[2:3]
	s_add_u32 m0, s4, 0xe000
	s_nop 0
	global_load_lds_dwordx4 v58, s[2:3]
	s_add_u32 m0, s4, 0xf000
	s_nop 0
	global_load_lds_dwordx4 v59, s[2:3]
	s_add_u32 s0, s0, 0x80
	s_addc_u32 s1, s1, 0
	s_add_u32 s2, s2, 0x80
	s_addc_u32 s3, s3, 0
	s_waitcnt vmcnt(8)
	s_barrier
	ds_read_b128 v[140:143], v66 offset:0
	ds_read_b128 v[144:147], v66 offset:2048
	ds_read_b128 v[148:151], v66 offset:4096
	ds_read_b128 v[152:155], v66 offset:6144
	ds_read_b128 v[156:159], v64 offset:0
	ds_read_b128 v[160:163], v64 offset:2048
	ds_read_b128 v[164:167], v64 offset:4096
	ds_read_b128 v[168:171], v64 offset:6144
	ds_read_b128 v[172:175], v67 offset:0
	ds_read_b128 v[176:179], v67 offset:2048
	ds_read_b128 v[180:183], v67 offset:4096
	ds_read_b128 v[184:187], v67 offset:6144
	ds_read_b128 v[188:191], v65 offset:0
	ds_read_b128 v[192:195], v65 offset:2048
	ds_read_b128 v[196:199], v65 offset:4096
	ds_read_b128 v[200:203], v65 offset:6144
	s_waitcnt lgkmcnt(0)
	s_barrier
	v_mfma_f32_16x16x32_bf16 v[60:63], v[140:143], v[156:159], v[60:63]
	v_mfma_f32_16x16x32_bf16 v[68:71], v[140:143], v[160:163], v[68:71]
	s_add_u32 m0, s4, 0x0
	s_nop 0
	global_load_lds_dwordx4 v56, s[0:1]
	v_mfma_f32_16x16x32_bf16 v[52:55], v[140:143], v[164:167], v[52:55]
	v_mfma_f32_16x16x32_bf16 v[40:43], v[140:143], v[168:171], v[40:43]
	s_add_u32 m0, s4, 0x1000
	s_nop 0
	global_load_lds_dwordx4 v57, s[0:1]
	v_mfma_f32_16x16x32_bf16 v[72:75], v[144:147], v[156:159], v[72:75]
	v_mfma_f32_16x16x32_bf16 v[48:51], v[144:147], v[160:163], v[48:51]
	s_add_u32 m0, s4, 0x2000
	s_nop 0
	global_load_lds_dwordx4 v58, s[0:1]
	v_mfma_f32_16x16x32_bf16 v[44:47], v[144:147], v[164:167], v[44:47]
	v_mfma_f32_16x16x32_bf16 v[36:39], v[144:147], v[168:171], v[36:39]
	s_add_u32 m0, s4, 0x3000
	s_nop 0
	global_load_lds_dwordx4 v59, s[0:1]
	v_mfma_f32_16x16x32_bf16 v[32:35], v[148:151], v[156:159], v[32:35]
	v_mfma_f32_16x16x32_bf16 v[28:31], v[148:151], v[160:163], v[28:31]
	s_add_u32 m0, s4, 0x4000
	s_nop 0
	global_load_lds_dwordx4 v56, s[2:3]
	v_mfma_f32_16x16x32_bf16 v[24:27], v[148:151], v[164:167], v[24:27]
	v_mfma_f32_16x16x32_bf16 v[20:23], v[148:151], v[168:171], v[20:23]
	s_add_u32 m0, s4, 0x5000
	s_nop 0
	global_load_lds_dwordx4 v57, s[2:3]
	v_mfma_f32_16x16x32_bf16 v[16:19], v[152:155], v[156:159], v[16:19]
	v_mfma_f32_16x16x32_bf16 v[12:15], v[152:155], v[160:163], v[12:15]
	s_add_u32 m0, s4, 0x6000
	s_nop 0
	global_load_lds_dwordx4 v58, s[2:3]
	v_mfma_f32_16x16x32_bf16 v[8:11], v[152:155], v[164:167], v[8:11]
	v_mfma_f32_16x16x32_bf16 v[4:7], v[152:155], v[168:171], v[4:7]
	s_add_u32 m0, s4, 0x7000
	s_nop 0
	global_load_lds_dwordx4 v59, s[2:3]
	v_mfma_f32_16x16x32_bf16 v[60:63], v[172:175], v[188:191], v[60:63]
	v_mfma_f32_16x16x32_bf16 v[68:71], v[172:175], v[192:195], v[68:71]
	v_mfma_f32_16x16x32_bf16 v[52:55], v[172:175], v[196:199], v[52:55]
	v_mfma_f32_16x16x32_bf16 v[40:43], v[172:175], v[200:203], v[40:43]
	v_mfma_f32_16x16x32_bf16 v[72:75], v[176:179], v[188:191], v[72:75]
	v_mfma_f32_16x16x32_bf16 v[48:51], v[176:179], v[192:195], v[48:51]
	v_mfma_f32_16x16x32_bf16 v[44:47], v[176:179], v[196:199], v[44:47]
	v_mfma_f32_16x16x32_bf16 v[36:39], v[176:179], v[200:203], v[36:39]
	s_add_u32 s0, s0, 0x80
	s_addc_u32 s1, s1, 0
	s_add_u32 s2, s2, 0x80
	s_addc_u32 s3, s3, 0
	s_waitcnt vmcnt(8)
	s_barrier
	v_mfma_f32_16x16x32_bf16 v[32:35], v[180:183], v[188:191], v[32:35]
	ds_read_b128 v[220:223], v66 offset:32768
	ds_read_b128 v[224:227], v66 offset:34816
	v_mfma_f32_16x16x32_bf16 v[28:31], v[180:183], v[192:195], v[28:31]
	ds_read_b128 v[228:231], v66 offset:36864
	ds_read_b128 v[232:235], v66 offset:38912
	v_mfma_f32_16x16x32_bf16 v[24:27], v[180:183], v[196:199], v[24:27]
	ds_read_b128 v[236:239], v64 offset:32768
	ds_read_b128 v[240:243], v64 offset:34816
	v_mfma_f32_16x16x32_bf16 v[20:23], v[180:183], v[200:203], v[20:23]
	ds_read_b128 v[244:247], v64 offset:36864
	ds_read_b128 v[248:251], v64 offset:38912
	v_mfma_f32_16x16x32_bf16 v[16:19], v[184:187], v[188:191], v[16:19]
	ds_read_b128 v[112:115], v67 offset:32768
	ds_read_b128 v[116:119], v67 offset:34816
	v_mfma_f32_16x16x32_bf16 v[12:15], v[184:187], v[192:195], v[12:15]
	ds_read_b128 v[120:123], v67 offset:36864
	ds_read_b128 v[124:127], v67 offset:38912
	v_mfma_f32_16x16x32_bf16 v[8:11], v[184:187], v[196:199], v[8:11]
	ds_read_b128 v[76:79], v65 offset:32768
	ds_read_b128 v[80:83], v65 offset:34816
	v_mfma_f32_16x16x32_bf16 v[4:7], v[184:187], v[200:203], v[4:7]
	ds_read_b128 v[84:87], v65 offset:36864
	ds_read_b128 v[88:91], v65 offset:38912
	s_waitcnt lgkmcnt(0)
	s_barrier
	v_mfma_f32_16x16x32_bf16 v[60:63], v[220:223], v[236:239], v[60:63]
	v_mfma_f32_16x16x32_bf16 v[68:71], v[220:223], v[240:243], v[68:71]
	s_add_u32 m0, s4, 0x8000
	s_nop 0
	global_load_lds_dwordx4 v56, s[0:1]
	v_mfma_f32_16x16x32_bf16 v[52:55], v[220:223], v[244:247], v[52:55]
	v_mfma_f32_16x16x32_bf16 v[40:43], v[220:223], v[248:251], v[40:43]
	s_add_u32 m0, s4, 0x9000
	s_nop 0
	global_load_lds_dwordx4 v57, s[0:1]
	v_mfma_f32_16x16x32_bf16 v[72:75], v[224:227], v[236:239], v[72:75]
	v_mfma_f32_16x16x32_bf16 v[48:51], v[224:227], v[240:243], v[48:51]
	s_add_u32 m0, s4, 0xa000
	s_nop 0
	global_load_lds_dwordx4 v58, s[0:1]
	v_mfma_f32_16x16x32_bf16 v[44:47], v[224:227], v[244:247], v[44:47]
	v_mfma_f32_16x16x32_bf16 v[36:39], v[224:227], v[248:251], v[36:39]
	s_add_u32 m0, s4, 0xb000
	s_nop 0
	global_load_lds_dwordx4 v59, s[0:1]
	v_mfma_f32_16x16x32_bf16 v[32:35], v[228:231], v[236:239], v[32:35]
	v_mfma_f32_16x16x32_bf16 v[28:31], v[228:231], v[240:243], v[28:31]
	s_add_u32 m0, s4, 0xc000
	s_nop 0
	global_load_lds_dwordx4 v56, s[2:3]
	v_mfma_f32_16x16x32_bf16 v[24:27], v[228:231], v[244:247], v[24:27]
	v_mfma_f32_16x16x32_bf16 v[20:23], v[228:231], v[248:251], v[20:23]
	s_add_u32 m0, s4, 0xd000
	s_nop 0
	global_load_lds_dwordx4 v57, s[2:3]
	v_mfma_f32_16x16x32_bf16 v[16:19], v[232:235], v[236:239], v[16:19]
	v_mfma_f32_16x16x32_bf16 v[12:15], v[232:235], v[240:243], v[12:15]
	s_add_u32 m0, s4, 0xe000
	s_nop 0
	global_load_lds_dwordx4 v58, s[2:3]
	v_mfma_f32_16x16x32_bf16 v[8:11], v[232:235], v[244:247], v[8:11]
	v_mfma_f32_16x16x32_bf16 v[4:7], v[232:235], v[248:251], v[4:7]
	s_add_u32 m0, s4, 0xf000
	s_nop 0
	global_load_lds_dwordx4 v59, s[2:3]
	v_mfma_f32_16x16x32_bf16 v[60:63], v[112:115], v[76:79], v[60:63]
	v_mfma_f32_16x16x32_bf16 v[68:71], v[112:115], v[80:83], v[68:71]
	v_mfma_f32_16x16x32_bf16 v[52:55], v[112:115], v[84:87], v[52:55]
	v_mfma_f32_16x16x32_bf16 v[40:43], v[112:115], v[88:91], v[40:43]
	v_mfma_f32_16x16x32_bf16 v[72:75], v[116:119], v[76:79], v[72:75]
	v_mfma_f32_16x16x32_bf16 v[48:51], v[116:119], v[80:83], v[48:51]
	v_mfma_f32_16x16x32_bf16 v[44:47], v[116:119], v[84:87], v[44:47]
	v_mfma_f32_16x16x32_bf16 v[36:39], v[116:119], v[88:91], v[36:39]
	s_add_u32 s0, s0, 0x80
	s_addc_u32 s1, s1, 0
	s_add_u32 s2, s2, 0x80
	s_addc_u32 s3, s3, 0
	s_waitcnt vmcnt(8)
	s_barrier
	v_mfma_f32_16x16x32_bf16 v[32:35], v[120:123], v[76:79], v[32:35]
	ds_read_b128 v[140:143], v66 offset:0
	ds_read_b128 v[144:147], v66 offset:2048
	v_mfma_f32_16x16x32_bf16 v[28:31], v[120:123], v[80:83], v[28:31]
	ds_read_b128 v[148:151], v66 offset:4096
	ds_read_b128 v[152:155], v66 offset:6144
	v_mfma_f32_16x16x32_bf16 v[24:27], v[120:123], v[84:87], v[24:27]
	ds_read_b128 v[156:159], v64 offset:0
	ds_read_b128 v[160:163], v64 offset:2048
	v_mfma_f32_16x16x32_bf16 v[20:23], v[120:123], v[88:91], v[20:23]
	ds_read_b128 v[164:167], v64 offset:4096
	ds_read_b128 v[168:171], v64 offset:6144
	v_mfma_f32_16x16x32_bf16 v[16:19], v[124:127], v[76:79], v[16:19]
	ds_read_b128 v[172:175], v67 offset:0
	ds_read_b128 v[176:179], v67 offset:2048
	v_mfma_f32_16x16x32_bf16 v[12:15], v[124:127], v[80:83], v[12:15]
	ds_read_b128 v[180:183], v67 offset:4096
	ds_read_b128 v[184:187], v67 offset:6144
	v_mfma_f32_16x16x32_bf16 v[8:11], v[124:127], v[84:87], v[8:11]
	ds_read_b128 v[188:191], v65 offset:0
	ds_read_b128 v[192:195], v65 offset:2048
	v_mfma_f32_16x16x32_bf16 v[4:7], v[124:127], v[88:91], v[4:7]
	ds_read_b128 v[196:199], v65 offset:4096
	ds_read_b128 v[200:203], v65 offset:6144
	s_waitcnt lgkmcnt(0)
	s_barrier
	v_mfma_f32_16x16x32_bf16 v[60:63], v[140:143], v[156:159], v[60:63]
	v_mfma_f32_16x16x32_bf16 v[68:71], v[140:143], v[160:163], v[68:71]
	s_add_u32 m0, s4, 0x0
	s_nop 0
	global_load_lds_dwordx4 v56, s[0:1]
	v_mfma_f32_16x16x32_bf16 v[52:55], v[140:143], v[164:167], v[52:55]
	v_mfma_f32_16x16x32_bf16 v[40:43], v[140:143], v[168:171], v[40:43]
	s_add_u32 m0, s4, 0x1000
	s_nop 0
	global_load_lds_dwordx4 v57, s[0:1]
	v_mfma_f32_16x16x32_bf16 v[72:75], v[144:147], v[156:159], v[72:75]
	v_mfma_f32_16x16x32_bf16 v[48:51], v[144:147], v[160:163], v[48:51]
	s_add_u32 m0, s4, 0x2000
	s_nop 0
	global_load_lds_dwordx4 v58, s[0:1]
	v_mfma_f32_16x16x32_bf16 v[44:47], v[144:147], v[164:167], v[44:47]
	v_mfma_f32_16x16x32_bf16 v[36:39], v[144:147], v[168:171], v[36:39]
	s_add_u32 m0, s4, 0x3000
	s_nop 0
	global_load_lds_dwordx4 v59, s[0:1]
	v_mfma_f32_16x16x32_bf16 v[32:35], v[148:151], v[156:159], v[32:35]
	v_mfma_f32_16x16x32_bf16 v[28:31], v[148:151], v[160:163], v[28:31]
	s_add_u32 m0, s4, 0x4000
	s_nop 0
	global_load_lds_dwordx4 v56, s[2:3]
	v_mfma_f32_16x16x32_bf16 v[24:27], v[148:151], v[164:167], v[24:27]
	v_mfma_f32_16x16x32_bf16 v[20:23], v[148:151], v[168:171], v[20:23]
	s_add_u32 m0, s4, 0x5000
	s_nop 0
	global_load_lds_dwordx4 v57, s[2:3]
	v_mfma_f32_16x16x32_bf16 v[16:19], v[152:155], v[156:159], v[16:19]
	v_mfma_f32_16x16x32_bf16 v[12:15], v[152:155], v[160:163], v[12:15]
	s_add_u32 m0, s4, 0x6000
	s_nop 0
	global_load_lds_dwordx4 v58, s[2:3]
	v_mfma_f32_16x16x32_bf16 v[8:11], v[152:155], v[164:167], v[8:11]
	v_mfma_f32_16x16x32_bf16 v[4:7], v[152:155], v[168:171], v[4:7]
	s_add_u32 m0, s4, 0x7000
	s_nop 0
	global_load_lds_dwordx4 v59, s[2:3]
	v_mfma_f32_16x16x32_bf16 v[60:63], v[172:175], v[188:191], v[60:63]
	v_mfma_f32_16x16x32_bf16 v[68:71], v[172:175], v[192:195], v[68:71]
	v_mfma_f32_16x16x32_bf16 v[52:55], v[172:175], v[196:199], v[52:55]
	v_mfma_f32_16x16x32_bf16 v[40:43], v[172:175], v[200:203], v[40:43]
	v_mfma_f32_16x16x32_bf16 v[72:75], v[176:179], v[188:191], v[72:75]
	v_mfma_f32_16x16x32_bf16 v[48:51], v[176:179], v[192:195], v[48:51]
	v_mfma_f32_16x16x32_bf16 v[44:47], v[176:179], v[196:199], v[44:47]
	v_mfma_f32_16x16x32_bf16 v[36:39], v[176:179], v[200:203], v[36:39]
	s_add_u32 s0, s0, 0x80
	s_addc_u32 s1, s1, 0
	s_add_u32 s2, s2, 0x80
	s_addc_u32 s3, s3, 0
	s_waitcnt vmcnt(8)
	s_barrier
	v_mfma_f32_16x16x32_bf16 v[32:35], v[180:183], v[188:191], v[32:35]
	ds_read_b128 v[220:223], v66 offset:32768
	ds_read_b128 v[224:227], v66 offset:34816
	v_mfma_f32_16x16x32_bf16 v[28:31], v[180:183], v[192:195], v[28:31]
	ds_read_b128 v[228:231], v66 offset:36864
	ds_read_b128 v[232:235], v66 offset:38912
	v_mfma_f32_16x16x32_bf16 v[24:27], v[180:183], v[196:199], v[24:27]
	ds_read_b128 v[236:239], v64 offset:32768
	ds_read_b128 v[240:243], v64 offset:34816
	v_mfma_f32_16x16x32_bf16 v[20:23], v[180:183], v[200:203], v[20:23]
	ds_read_b128 v[244:247], v64 offset:36864
	ds_read_b128 v[248:251], v64 offset:38912
	v_mfma_f32_16x16x32_bf16 v[16:19], v[184:187], v[188:191], v[16:19]
	ds_read_b128 v[112:115], v67 offset:32768
	ds_read_b128 v[116:119], v67 offset:34816
	v_mfma_f32_16x16x32_bf16 v[12:15], v[184:187], v[192:195], v[12:15]
	ds_read_b128 v[120:123], v67 offset:36864
	ds_read_b128 v[124:127], v67 offset:38912
	v_mfma_f32_16x16x32_bf16 v[8:11], v[184:187], v[196:199], v[8:11]
	ds_read_b128 v[76:79], v65 offset:32768
	ds_read_b128 v[80:83], v65 offset:34816
	v_mfma_f32_16x16x32_bf16 v[4:7], v[184:187], v[200:203], v[4:7]
	ds_read_b128 v[84:87], v65 offset:36864
	ds_read_b128 v[88:91], v65 offset:38912
	s_waitcnt lgkmcnt(0)
	s_barrier
	v_mfma_f32_16x16x32_bf16 v[60:63], v[220:223], v[236:239], v[60:63]
	v_mfma_f32_16x16x32_bf16 v[68:71], v[220:223], v[240:243], v[68:71]
	s_add_u32 m0, s4, 0x8000
	s_nop 0
	global_load_lds_dwordx4 v56, s[0:1]
	v_mfma_f32_16x16x32_bf16 v[52:55], v[220:223], v[244:247], v[52:55]
	v_mfma_f32_16x16x32_bf16 v[40:43], v[220:223], v[248:251], v[40:43]
	s_add_u32 m0, s4, 0x9000
	s_nop 0
	global_load_lds_dwordx4 v57, s[0:1]
	v_mfma_f32_16x16x32_bf16 v[72:75], v[224:227], v[236:239], v[72:75]
	v_mfma_f32_16x16x32_bf16 v[48:51], v[224:227], v[240:243], v[48:51]
	s_add_u32 m0, s4, 0xa000
	s_nop 0
	global_load_lds_dwordx4 v58, s[0:1]
	v_mfma_f32_16x16x32_bf16 v[44:47], v[224:227], v[244:247], v[44:47]
	v_mfma_f32_16x16x32_bf16 v[36:39], v[224:227], v[248:251], v[36:39]
	s_add_u32 m0, s4, 0xb000
	s_nop 0
	global_load_lds_dwordx4 v59, s[0:1]
	v_mfma_f32_16x16x32_bf16 v[32:35], v[228:231], v[236:239], v[32:35]
	v_mfma_f32_16x16x32_bf16 v[28:31], v[228:231], v[240:243], v[28:31]
	s_add_u32 m0, s4, 0xc000
	s_nop 0
	global_load_lds_dwordx4 v56, s[2:3]
	v_mfma_f32_16x16x32_bf16 v[24:27], v[228:231], v[244:247], v[24:27]
	v_mfma_f32_16x16x32_bf16 v[20:23], v[228:231], v[248:251], v[20:23]
	s_add_u32 m0, s4, 0xd000
	s_nop 0
	global_load_lds_dwordx4 v57, s[2:3]
	v_mfma_f32_16x16x32_bf16 v[16:19], v[232:235], v[236:239], v[16:19]
	v_mfma_f32_16x16x32_bf16 v[12:15], v[232:235], v[240:243], v[12:15]
	s_add_u32 m0, s4, 0xe000
	s_nop 0
	global_load_lds_dwordx4 v58, s[2:3]
	v_mfma_f32_16x16x32_bf16 v[8:11], v[232:235], v[244:247], v[8:11]
	v_mfma_f32_16x16x32_bf16 v[4:7], v[232:235], v[248:251], v[4:7]
	s_add_u32 m0, s4, 0xf000
	s_nop 0
	global_load_lds_dwordx4 v59, s[2:3]
	v_mfma_f32_16x16x32_bf16 v[60:63], v[112:115], v[76:79], v[60:63]
	v_mfma_f32_16x16x32_bf16 v[68:71], v[112:115], v[80:83], v[68:71]
	v_mfma_f32_16x16x32_bf16 v[52:55], v[112:115], v[84:87], v[52:55]
	v_mfma_f32_16x16x32_bf16 v[40:43], v[112:115], v[88:91], v[40:43]
	v_mfma_f32_16x16x32_bf16 v[72:75], v[116:119], v[76:79], v[72:75]
	v_mfma_f32_16x16x32_bf16 v[48:51], v[116:119], v[80:83], v[48:51]
	v_mfma_f32_16x16x32_bf16 v[44:47], v[116:119], v[84:87], v[44:47]
	v_mfma_f32_16x16x32_bf16 v[36:39], v[116:119], v[88:91], v[36:39]
	s_add_u32 s0, s0, 0x80
	s_addc_u32 s1, s1, 0
	s_add_u32 s2, s2, 0x80
	s_addc_u32 s3, s3, 0
	s_waitcnt vmcnt(8)
	s_barrier
	v_mfma_f32_16x16x32_bf16 v[32:35], v[120:123], v[76:79], v[32:35]
	ds_read_b128 v[140:143], v66 offset:0
	ds_read_b128 v[144:147], v66 offset:2048
	v_mfma_f32_16x16x32_bf16 v[28:31], v[120:123], v[80:83], v[28:31]
	ds_read_b128 v[148:151], v66 offset:4096
	ds_read_b128 v[152:155], v66 offset:6144
	v_mfma_f32_16x16x32_bf16 v[24:27], v[120:123], v[84:87], v[24:27]
	ds_read_b128 v[156:159], v64 offset:0
	ds_read_b128 v[160:163], v64 offset:2048
	v_mfma_f32_16x16x32_bf16 v[20:23], v[120:123], v[88:91], v[20:23]
	ds_read_b128 v[164:167], v64 offset:4096
	ds_read_b128 v[168:171], v64 offset:6144
	v_mfma_f32_16x16x32_bf16 v[16:19], v[124:127], v[76:79], v[16:19]
	ds_read_b128 v[172:175], v67 offset:0
	ds_read_b128 v[176:179], v67 offset:2048
	v_mfma_f32_16x16x32_bf16 v[12:15], v[124:127], v[80:83], v[12:15]
	ds_read_b128 v[180:183], v67 offset:4096
	ds_read_b128 v[184:187], v67 offset:6144
	v_mfma_f32_16x16x32_bf16 v[8:11], v[124:127], v[84:87], v[8:11]
	ds_read_b128 v[188:191], v65 offset:0
	ds_read_b128 v[192:195], v65 offset:2048
	v_mfma_f32_16x16x32_bf16 v[4:7], v[124:127], v[88:91], v[4:7]
	ds_read_b128 v[196:199], v65 offset:4096
	ds_read_b128 v[200:203], v65 offset:6144
	s_waitcnt lgkmcnt(0)
	s_barrier
	v_mfma_f32_16x16x32_bf16 v[60:63], v[140:143], v[156:159], v[60:63]
	v_mfma_f32_16x16x32_bf16 v[68:71], v[140:143], v[160:163], v[68:71]
	s_add_u32 m0, s4, 0x0
	s_nop 0
	global_load_lds_dwordx4 v56, s[0:1]
	v_mfma_f32_16x16x32_bf16 v[52:55], v[140:143], v[164:167], v[52:55]
	v_mfma_f32_16x16x32_bf16 v[40:43], v[140:143], v[168:171], v[40:43]
	s_add_u32 m0, s4, 0x1000
	s_nop 0
	global_load_lds_dwordx4 v57, s[0:1]
	v_mfma_f32_16x16x32_bf16 v[72:75], v[144:147], v[156:159], v[72:75]
	v_mfma_f32_16x16x32_bf16 v[48:51], v[144:147], v[160:163], v[48:51]
	s_add_u32 m0, s4, 0x2000
	s_nop 0
	global_load_lds_dwordx4 v58, s[0:1]
	v_mfma_f32_16x16x32_bf16 v[44:47], v[144:147], v[164:167], v[44:47]
	v_mfma_f32_16x16x32_bf16 v[36:39], v[144:147], v[168:171], v[36:39]
	s_add_u32 m0, s4, 0x3000
	s_nop 0
	global_load_lds_dwordx4 v59, s[0:1]
	v_mfma_f32_16x16x32_bf16 v[32:35], v[148:151], v[156:159], v[32:35]
	v_mfma_f32_16x16x32_bf16 v[28:31], v[148:151], v[160:163], v[28:31]
	s_add_u32 m0, s4, 0x4000
	s_nop 0
	global_load_lds_dwordx4 v56, s[2:3]
	v_mfma_f32_16x16x32_bf16 v[24:27], v[148:151], v[164:167], v[24:27]
	v_mfma_f32_16x16x32_bf16 v[20:23], v[148:151], v[168:171], v[20:23]
	s_add_u32 m0, s4, 0x5000
	s_nop 0
	global_load_lds_dwordx4 v57, s[2:3]
	v_mfma_f32_16x16x32_bf16 v[16:19], v[152:155], v[156:159], v[16:19]
	v_mfma_f32_16x16x32_bf16 v[12:15], v[152:155], v[160:163], v[12:15]
	s_add_u32 m0, s4, 0x6000
	s_nop 0
	global_load_lds_dwordx4 v58, s[2:3]
	v_mfma_f32_16x16x32_bf16 v[8:11], v[152:155], v[164:167], v[8:11]
	v_mfma_f32_16x16x32_bf16 v[4:7], v[152:155], v[168:171], v[4:7]
	s_add_u32 m0, s4, 0x7000
	s_nop 0
	global_load_lds_dwordx4 v59, s[2:3]
	v_mfma_f32_16x16x32_bf16 v[60:63], v[172:175], v[188:191], v[60:63]
	v_mfma_f32_16x16x32_bf16 v[68:71], v[172:175], v[192:195], v[68:71]
	v_mfma_f32_16x16x32_bf16 v[52:55], v[172:175], v[196:199], v[52:55]
	v_mfma_f32_16x16x32_bf16 v[40:43], v[172:175], v[200:203], v[40:43]
	v_mfma_f32_16x16x32_bf16 v[72:75], v[176:179], v[188:191], v[72:75]
	v_mfma_f32_16x16x32_bf16 v[48:51], v[176:179], v[192:195], v[48:51]
	v_mfma_f32_16x16x32_bf16 v[44:47], v[176:179], v[196:199], v[44:47]
	v_mfma_f32_16x16x32_bf16 v[36:39], v[176:179], v[200:203], v[36:39]
	s_add_u32 s0, s0, 0x80
	s_addc_u32 s1, s1, 0
	s_add_u32 s2, s2, 0x80
	s_addc_u32 s3, s3, 0
	s_waitcnt vmcnt(8)
	s_barrier
	v_mfma_f32_16x16x32_bf16 v[32:35], v[180:183], v[188:191], v[32:35]
	ds_read_b128 v[220:223], v66 offset:32768
	ds_read_b128 v[224:227], v66 offset:34816
	v_mfma_f32_16x16x32_bf16 v[28:31], v[180:183], v[192:195], v[28:31]
	ds_read_b128 v[228:231], v66 offset:36864
	ds_read_b128 v[232:235], v66 offset:38912
	v_mfma_f32_16x16x32_bf16 v[24:27], v[180:183], v[196:199], v[24:27]
	ds_read_b128 v[236:239], v64 offset:32768
	ds_read_b128 v[240:243], v64 offset:34816
	v_mfma_f32_16x16x32_bf16 v[20:23], v[180:183], v[200:203], v[20:23]
	ds_read_b128 v[244:247], v64 offset:36864
	ds_read_b128 v[248:251], v64 offset:38912
	v_mfma_f32_16x16x32_bf16 v[16:19], v[184:187], v[188:191], v[16:19]
	ds_read_b128 v[112:115], v67 offset:32768
	ds_read_b128 v[116:119], v67 offset:34816
	v_mfma_f32_16x16x32_bf16 v[12:15], v[184:187], v[192:195], v[12:15]
	ds_read_b128 v[120:123], v67 offset:36864
	ds_read_b128 v[124:127], v67 offset:38912
	v_mfma_f32_16x16x32_bf16 v[8:11], v[184:187], v[196:199], v[8:11]
	ds_read_b128 v[76:79], v65 offset:32768
	ds_read_b128 v[80:83], v65 offset:34816
	v_mfma_f32_16x16x32_bf16 v[4:7], v[184:187], v[200:203], v[4:7]
	ds_read_b128 v[84:87], v65 offset:36864
	ds_read_b128 v[88:91], v65 offset:38912
	s_waitcnt lgkmcnt(0)
	s_barrier
	v_mfma_f32_16x16x32_bf16 v[60:63], v[220:223], v[236:239], v[60:63]
	v_mfma_f32_16x16x32_bf16 v[68:71], v[220:223], v[240:243], v[68:71]
	s_add_u32 m0, s4, 0x8000
	s_nop 0
	global_load_lds_dwordx4 v56, s[0:1]
	v_mfma_f32_16x16x32_bf16 v[52:55], v[220:223], v[244:247], v[52:55]
	v_mfma_f32_16x16x32_bf16 v[40:43], v[220:223], v[248:251], v[40:43]
	s_add_u32 m0, s4, 0x9000
	s_nop 0
	global_load_lds_dwordx4 v57, s[0:1]
	v_mfma_f32_16x16x32_bf16 v[72:75], v[224:227], v[236:239], v[72:75]
	v_mfma_f32_16x16x32_bf16 v[48:51], v[224:227], v[240:243], v[48:51]
	s_add_u32 m0, s4, 0xa000
	s_nop 0
	global_load_lds_dwordx4 v58, s[0:1]
	v_mfma_f32_16x16x32_bf16 v[44:47], v[224:227], v[244:247], v[44:47]
	v_mfma_f32_16x16x32_bf16 v[36:39], v[224:227], v[248:251], v[36:39]
	s_add_u32 m0, s4, 0xb000
	s_nop 0
	global_load_lds_dwordx4 v59, s[0:1]
	v_mfma_f32_16x16x32_bf16 v[32:35], v[228:231], v[236:239], v[32:35]
	v_mfma_f32_16x16x32_bf16 v[28:31], v[228:231], v[240:243], v[28:31]
	s_add_u32 m0, s4, 0xc000
	s_nop 0
	global_load_lds_dwordx4 v56, s[2:3]
	v_mfma_f32_16x16x32_bf16 v[24:27], v[228:231], v[244:247], v[24:27]
	v_mfma_f32_16x16x32_bf16 v[20:23], v[228:231], v[248:251], v[20:23]
	s_add_u32 m0, s4, 0xd000
	s_nop 0
	global_load_lds_dwordx4 v57, s[2:3]
	v_mfma_f32_16x16x32_bf16 v[16:19], v[232:235], v[236:239], v[16:19]
	v_mfma_f32_16x16x32_bf16 v[12:15], v[232:235], v[240:243], v[12:15]
	s_add_u32 m0, s4, 0xe000
	s_nop 0
	global_load_lds_dwordx4 v58, s[2:3]
	v_mfma_f32_16x16x32_bf16 v[8:11], v[232:235], v[244:247], v[8:11]
	v_mfma_f32_16x16x32_bf16 v[4:7], v[232:235], v[248:251], v[4:7]
	s_add_u32 m0, s4, 0xf000
	s_nop 0
	global_load_lds_dwordx4 v59, s[2:3]
	v_mfma_f32_16x16x32_bf16 v[60:63], v[112:115], v[76:79], v[60:63]
	v_mfma_f32_16x16x32_bf16 v[68:71], v[112:115], v[80:83], v[68:71]
	v_mfma_f32_16x16x32_bf16 v[52:55], v[112:115], v[84:87], v[52:55]
	v_mfma_f32_16x16x32_bf16 v[40:43], v[112:115], v[88:91], v[40:43]
	v_mfma_f32_16x16x32_bf16 v[72:75], v[116:119], v[76:79], v[72:75]
	v_mfma_f32_16x16x32_bf16 v[48:51], v[116:119], v[80:83], v[48:51]
	v_mfma_f32_16x16x32_bf16 v[44:47], v[116:119], v[84:87], v[44:47]
	v_mfma_f32_16x16x32_bf16 v[36:39], v[116:119], v[88:91], v[36:39]
	s_add_u32 s0, s0, 0x80
	s_addc_u32 s1, s1, 0
	s_add_u32 s2, s2, 0x80
	s_addc_u32 s3, s3, 0
	s_waitcnt vmcnt(8)
	s_barrier
	v_mfma_f32_16x16x32_bf16 v[32:35], v[120:123], v[76:79], v[32:35]
	ds_read_b128 v[140:143], v66 offset:0
	ds_read_b128 v[144:147], v66 offset:2048
	v_mfma_f32_16x16x32_bf16 v[28:31], v[120:123], v[80:83], v[28:31]
	ds_read_b128 v[148:151], v66 offset:4096
	ds_read_b128 v[152:155], v66 offset:6144
	v_mfma_f32_16x16x32_bf16 v[24:27], v[120:123], v[84:87], v[24:27]
	ds_read_b128 v[156:159], v64 offset:0
	ds_read_b128 v[160:163], v64 offset:2048
	v_mfma_f32_16x16x32_bf16 v[20:23], v[120:123], v[88:91], v[20:23]
	ds_read_b128 v[164:167], v64 offset:4096
	ds_read_b128 v[168:171], v64 offset:6144
	v_mfma_f32_16x16x32_bf16 v[16:19], v[124:127], v[76:79], v[16:19]
	ds_read_b128 v[172:175], v67 offset:0
	ds_read_b128 v[176:179], v67 offset:2048
	v_mfma_f32_16x16x32_bf16 v[12:15], v[124:127], v[80:83], v[12:15]
	ds_read_b128 v[180:183], v67 offset:4096
	ds_read_b128 v[184:187], v67 offset:6144
	v_mfma_f32_16x16x32_bf16 v[8:11], v[124:127], v[84:87], v[8:11]
	ds_read_b128 v[188:191], v65 offset:0
	ds_read_b128 v[192:195], v65 offset:2048
	v_mfma_f32_16x16x32_bf16 v[4:7], v[124:127], v[88:91], v[4:7]
	ds_read_b128 v[196:199], v65 offset:4096
	ds_read_b128 v[200:203], v65 offset:6144
	s_waitcnt lgkmcnt(0)
	s_barrier
	v_mfma_f32_16x16x32_bf16 v[60:63], v[140:143], v[156:159], v[60:63]
	v_mfma_f32_16x16x32_bf16 v[68:71], v[140:143], v[160:163], v[68:71]
	s_add_u32 m0, s4, 0x0
	s_nop 0
	global_load_lds_dwordx4 v56, s[0:1]
	v_mfma_f32_16x16x32_bf16 v[52:55], v[140:143], v[164:167], v[52:55]
	v_mfma_f32_16x16x32_bf16 v[40:43], v[140:143], v[168:171], v[40:43]
	s_add_u32 m0, s4, 0x1000
	s_nop 0
	global_load_lds_dwordx4 v57, s[0:1]
	v_mfma_f32_16x16x32_bf16 v[72:75], v[144:147], v[156:159], v[72:75]
	v_mfma_f32_16x16x32_bf16 v[48:51], v[144:147], v[160:163], v[48:51]
	s_add_u32 m0, s4, 0x2000
	s_nop 0
	global_load_lds_dwordx4 v58, s[0:1]
	v_mfma_f32_16x16x32_bf16 v[44:47], v[144:147], v[164:167], v[44:47]
	v_mfma_f32_16x16x32_bf16 v[36:39], v[144:147], v[168:171], v[36:39]
	s_add_u32 m0, s4, 0x3000
	s_nop 0
	global_load_lds_dwordx4 v59, s[0:1]
	v_mfma_f32_16x16x32_bf16 v[32:35], v[148:151], v[156:159], v[32:35]
	v_mfma_f32_16x16x32_bf16 v[28:31], v[148:151], v[160:163], v[28:31]
	s_add_u32 m0, s4, 0x4000
	s_nop 0
	global_load_lds_dwordx4 v56, s[2:3]
	v_mfma_f32_16x16x32_bf16 v[24:27], v[148:151], v[164:167], v[24:27]
	v_mfma_f32_16x16x32_bf16 v[20:23], v[148:151], v[168:171], v[20:23]
	s_add_u32 m0, s4, 0x5000
	s_nop 0
	global_load_lds_dwordx4 v57, s[2:3]
	v_mfma_f32_16x16x32_bf16 v[16:19], v[152:155], v[156:159], v[16:19]
	v_mfma_f32_16x16x32_bf16 v[12:15], v[152:155], v[160:163], v[12:15]
	s_add_u32 m0, s4, 0x6000
	s_nop 0
	global_load_lds_dwordx4 v58, s[2:3]
	v_mfma_f32_16x16x32_bf16 v[8:11], v[152:155], v[164:167], v[8:11]
	v_mfma_f32_16x16x32_bf16 v[4:7], v[152:155], v[168:171], v[4:7]
	s_add_u32 m0, s4, 0x7000
	s_nop 0
	global_load_lds_dwordx4 v59, s[2:3]
	v_mfma_f32_16x16x32_bf16 v[60:63], v[172:175], v[188:191], v[60:63]
	v_mfma_f32_16x16x32_bf16 v[68:71], v[172:175], v[192:195], v[68:71]
	v_mfma_f32_16x16x32_bf16 v[52:55], v[172:175], v[196:199], v[52:55]
	v_mfma_f32_16x16x32_bf16 v[40:43], v[172:175], v[200:203], v[40:43]
	v_mfma_f32_16x16x32_bf16 v[72:75], v[176:179], v[188:191], v[72:75]
	v_mfma_f32_16x16x32_bf16 v[48:51], v[176:179], v[192:195], v[48:51]
	v_mfma_f32_16x16x32_bf16 v[44:47], v[176:179], v[196:199], v[44:47]
	v_mfma_f32_16x16x32_bf16 v[36:39], v[176:179], v[200:203], v[36:39]
	s_add_u32 s0, s0, 0x80
	s_addc_u32 s1, s1, 0
	s_add_u32 s2, s2, 0x80
	s_addc_u32 s3, s3, 0
	s_waitcnt vmcnt(8)
	s_barrier
	v_mfma_f32_16x16x32_bf16 v[32:35], v[180:183], v[188:191], v[32:35]
	ds_read_b128 v[220:223], v66 offset:32768
	ds_read_b128 v[224:227], v66 offset:34816
	v_mfma_f32_16x16x32_bf16 v[28:31], v[180:183], v[192:195], v[28:31]
	ds_read_b128 v[228:231], v66 offset:36864
	ds_read_b128 v[232:235], v66 offset:38912
	v_mfma_f32_16x16x32_bf16 v[24:27], v[180:183], v[196:199], v[24:27]
	ds_read_b128 v[236:239], v64 offset:32768
	ds_read_b128 v[240:243], v64 offset:34816
	v_mfma_f32_16x16x32_bf16 v[20:23], v[180:183], v[200:203], v[20:23]
	ds_read_b128 v[244:247], v64 offset:36864
	ds_read_b128 v[248:251], v64 offset:38912
	v_mfma_f32_16x16x32_bf16 v[16:19], v[184:187], v[188:191], v[16:19]
	ds_read_b128 v[112:115], v67 offset:32768
	ds_read_b128 v[116:119], v67 offset:34816
	v_mfma_f32_16x16x32_bf16 v[12:15], v[184:187], v[192:195], v[12:15]
	ds_read_b128 v[120:123], v67 offset:36864
	ds_read_b128 v[124:127], v67 offset:38912
	v_mfma_f32_16x16x32_bf16 v[8:11], v[184:187], v[196:199], v[8:11]
	ds_read_b128 v[76:79], v65 offset:32768
	ds_read_b128 v[80:83], v65 offset:34816
	v_mfma_f32_16x16x32_bf16 v[4:7], v[184:187], v[200:203], v[4:7]
	ds_read_b128 v[84:87], v65 offset:36864
	ds_read_b128 v[88:91], v65 offset:38912
	s_waitcnt lgkmcnt(0)
	s_barrier
	v_mfma_f32_16x16x32_bf16 v[60:63], v[220:223], v[236:239], v[60:63]
	v_mfma_f32_16x16x32_bf16 v[68:71], v[220:223], v[240:243], v[68:71]
	s_add_u32 m0, s4, 0x8000
	s_nop 0
	global_load_lds_dwordx4 v56, s[0:1]
	v_mfma_f32_16x16x32_bf16 v[52:55], v[220:223], v[244:247], v[52:55]
	v_mfma_f32_16x16x32_bf16 v[40:43], v[220:223], v[248:251], v[40:43]
	s_add_u32 m0, s4, 0x9000
	s_nop 0
	global_load_lds_dwordx4 v57, s[0:1]
	v_mfma_f32_16x16x32_bf16 v[72:75], v[224:227], v[236:239], v[72:75]
	v_mfma_f32_16x16x32_bf16 v[48:51], v[224:227], v[240:243], v[48:51]
	s_add_u32 m0, s4, 0xa000
	s_nop 0
	global_load_lds_dwordx4 v58, s[0:1]
	v_mfma_f32_16x16x32_bf16 v[44:47], v[224:227], v[244:247], v[44:47]
	v_mfma_f32_16x16x32_bf16 v[36:39], v[224:227], v[248:251], v[36:39]
	s_add_u32 m0, s4, 0xb000
	s_nop 0
	global_load_lds_dwordx4 v59, s[0:1]
	v_mfma_f32_16x16x32_bf16 v[32:35], v[228:231], v[236:239], v[32:35]
	v_mfma_f32_16x16x32_bf16 v[28:31], v[228:231], v[240:243], v[28:31]
	s_add_u32 m0, s4, 0xc000
	s_nop 0
	global_load_lds_dwordx4 v56, s[2:3]
	v_mfma_f32_16x16x32_bf16 v[24:27], v[228:231], v[244:247], v[24:27]
	v_mfma_f32_16x16x32_bf16 v[20:23], v[228:231], v[248:251], v[20:23]
	s_add_u32 m0, s4, 0xd000
	s_nop 0
	global_load_lds_dwordx4 v57, s[2:3]
	v_mfma_f32_16x16x32_bf16 v[16:19], v[232:235], v[236:239], v[16:19]
	v_mfma_f32_16x16x32_bf16 v[12:15], v[232:235], v[240:243], v[12:15]
	s_add_u32 m0, s4, 0xe000
	s_nop 0
	global_load_lds_dwordx4 v58, s[2:3]
	v_mfma_f32_16x16x32_bf16 v[8:11], v[232:235], v[244:247], v[8:11]
	v_mfma_f32_16x16x32_bf16 v[4:7], v[232:235], v[248:251], v[4:7]
	s_add_u32 m0, s4, 0xf000
	s_nop 0
	global_load_lds_dwordx4 v59, s[2:3]
	v_mfma_f32_16x16x32_bf16 v[60:63], v[112:115], v[76:79], v[60:63]
	v_mfma_f32_16x16x32_bf16 v[68:71], v[112:115], v[80:83], v[68:71]
	v_mfma_f32_16x16x32_bf16 v[52:55], v[112:115], v[84:87], v[52:55]
	v_mfma_f32_16x16x32_bf16 v[40:43], v[112:115], v[88:91], v[40:43]
	v_mfma_f32_16x16x32_bf16 v[72:75], v[116:119], v[76:79], v[72:75]
	v_mfma_f32_16x16x32_bf16 v[48:51], v[116:119], v[80:83], v[48:51]
	v_mfma_f32_16x16x32_bf16 v[44:47], v[116:119], v[84:87], v[44:47]
	v_mfma_f32_16x16x32_bf16 v[36:39], v[116:119], v[88:91], v[36:39]
	s_add_u32 s0, s0, 0x80
	s_addc_u32 s1, s1, 0
	s_add_u32 s2, s2, 0x80
	s_addc_u32 s3, s3, 0
	s_waitcnt vmcnt(8)
	s_barrier
	v_mfma_f32_16x16x32_bf16 v[32:35], v[120:123], v[76:79], v[32:35]
	ds_read_b128 v[140:143], v66 offset:0
	ds_read_b128 v[144:147], v66 offset:2048
	v_mfma_f32_16x16x32_bf16 v[28:31], v[120:123], v[80:83], v[28:31]
	ds_read_b128 v[148:151], v66 offset:4096
	ds_read_b128 v[152:155], v66 offset:6144
	v_mfma_f32_16x16x32_bf16 v[24:27], v[120:123], v[84:87], v[24:27]
	ds_read_b128 v[156:159], v64 offset:0
	ds_read_b128 v[160:163], v64 offset:2048
	v_mfma_f32_16x16x32_bf16 v[20:23], v[120:123], v[88:91], v[20:23]
	ds_read_b128 v[164:167], v64 offset:4096
	ds_read_b128 v[168:171], v64 offset:6144
	v_mfma_f32_16x16x32_bf16 v[16:19], v[124:127], v[76:79], v[16:19]
	ds_read_b128 v[172:175], v67 offset:0
	ds_read_b128 v[176:179], v67 offset:2048
	v_mfma_f32_16x16x32_bf16 v[12:15], v[124:127], v[80:83], v[12:15]
	ds_read_b128 v[180:183], v67 offset:4096
	ds_read_b128 v[184:187], v67 offset:6144
	v_mfma_f32_16x16x32_bf16 v[8:11], v[124:127], v[84:87], v[8:11]
	ds_read_b128 v[188:191], v65 offset:0
	ds_read_b128 v[192:195], v65 offset:2048
	v_mfma_f32_16x16x32_bf16 v[4:7], v[124:127], v[88:91], v[4:7]
	ds_read_b128 v[196:199], v65 offset:4096
	ds_read_b128 v[200:203], v65 offset:6144
	s_waitcnt lgkmcnt(0)
	s_barrier
	v_mfma_f32_16x16x32_bf16 v[60:63], v[140:143], v[156:159], v[60:63]
	v_mfma_f32_16x16x32_bf16 v[68:71], v[140:143], v[160:163], v[68:71]
	s_add_u32 m0, s4, 0x0
	s_nop 0
	global_load_lds_dwordx4 v56, s[0:1]
	v_mfma_f32_16x16x32_bf16 v[52:55], v[140:143], v[164:167], v[52:55]
	v_mfma_f32_16x16x32_bf16 v[40:43], v[140:143], v[168:171], v[40:43]
	s_add_u32 m0, s4, 0x1000
	s_nop 0
	global_load_lds_dwordx4 v57, s[0:1]
	v_mfma_f32_16x16x32_bf16 v[72:75], v[144:147], v[156:159], v[72:75]
	v_mfma_f32_16x16x32_bf16 v[48:51], v[144:147], v[160:163], v[48:51]
	s_add_u32 m0, s4, 0x2000
	s_nop 0
	global_load_lds_dwordx4 v58, s[0:1]
	v_mfma_f32_16x16x32_bf16 v[44:47], v[144:147], v[164:167], v[44:47]
	v_mfma_f32_16x16x32_bf16 v[36:39], v[144:147], v[168:171], v[36:39]
	s_add_u32 m0, s4, 0x3000
	s_nop 0
	global_load_lds_dwordx4 v59, s[0:1]
	v_mfma_f32_16x16x32_bf16 v[32:35], v[148:151], v[156:159], v[32:35]
	v_mfma_f32_16x16x32_bf16 v[28:31], v[148:151], v[160:163], v[28:31]
	s_add_u32 m0, s4, 0x4000
	s_nop 0
	global_load_lds_dwordx4 v56, s[2:3]
	v_mfma_f32_16x16x32_bf16 v[24:27], v[148:151], v[164:167], v[24:27]
	v_mfma_f32_16x16x32_bf16 v[20:23], v[148:151], v[168:171], v[20:23]
	s_add_u32 m0, s4, 0x5000
	s_nop 0
	global_load_lds_dwordx4 v57, s[2:3]
	v_mfma_f32_16x16x32_bf16 v[16:19], v[152:155], v[156:159], v[16:19]
	v_mfma_f32_16x16x32_bf16 v[12:15], v[152:155], v[160:163], v[12:15]
	s_add_u32 m0, s4, 0x6000
	s_nop 0
	global_load_lds_dwordx4 v58, s[2:3]
	v_mfma_f32_16x16x32_bf16 v[8:11], v[152:155], v[164:167], v[8:11]
	v_mfma_f32_16x16x32_bf16 v[4:7], v[152:155], v[168:171], v[4:7]
	s_add_u32 m0, s4, 0x7000
	s_nop 0
	global_load_lds_dwordx4 v59, s[2:3]
	v_mfma_f32_16x16x32_bf16 v[60:63], v[172:175], v[188:191], v[60:63]
	v_mfma_f32_16x16x32_bf16 v[68:71], v[172:175], v[192:195], v[68:71]
	v_mfma_f32_16x16x32_bf16 v[52:55], v[172:175], v[196:199], v[52:55]
	v_mfma_f32_16x16x32_bf16 v[40:43], v[172:175], v[200:203], v[40:43]
	v_mfma_f32_16x16x32_bf16 v[72:75], v[176:179], v[188:191], v[72:75]
	v_mfma_f32_16x16x32_bf16 v[48:51], v[176:179], v[192:195], v[48:51]
	v_mfma_f32_16x16x32_bf16 v[44:47], v[176:179], v[196:199], v[44:47]
	v_mfma_f32_16x16x32_bf16 v[36:39], v[176:179], v[200:203], v[36:39]
	s_add_u32 s0, s0, 0x80
	s_addc_u32 s1, s1, 0
	s_add_u32 s2, s2, 0x80
	s_addc_u32 s3, s3, 0
	s_waitcnt vmcnt(8)
	s_barrier
	v_mfma_f32_16x16x32_bf16 v[32:35], v[180:183], v[188:191], v[32:35]
	ds_read_b128 v[220:223], v66 offset:32768
	ds_read_b128 v[224:227], v66 offset:34816
	v_mfma_f32_16x16x32_bf16 v[28:31], v[180:183], v[192:195], v[28:31]
	ds_read_b128 v[228:231], v66 offset:36864
	ds_read_b128 v[232:235], v66 offset:38912
	v_mfma_f32_16x16x32_bf16 v[24:27], v[180:183], v[196:199], v[24:27]
	ds_read_b128 v[236:239], v64 offset:32768
	ds_read_b128 v[240:243], v64 offset:34816
	v_mfma_f32_16x16x32_bf16 v[20:23], v[180:183], v[200:203], v[20:23]
	ds_read_b128 v[244:247], v64 offset:36864
	ds_read_b128 v[248:251], v64 offset:38912
	v_mfma_f32_16x16x32_bf16 v[16:19], v[184:187], v[188:191], v[16:19]
	ds_read_b128 v[112:115], v67 offset:32768
	ds_read_b128 v[116:119], v67 offset:34816
	v_mfma_f32_16x16x32_bf16 v[12:15], v[184:187], v[192:195], v[12:15]
	ds_read_b128 v[120:123], v67 offset:36864
	ds_read_b128 v[124:127], v67 offset:38912
	v_mfma_f32_16x16x32_bf16 v[8:11], v[184:187], v[196:199], v[8:11]
	ds_read_b128 v[76:79], v65 offset:32768
	ds_read_b128 v[80:83], v65 offset:34816
	v_mfma_f32_16x16x32_bf16 v[4:7], v[184:187], v[200:203], v[4:7]
	ds_read_b128 v[84:87], v65 offset:36864
	ds_read_b128 v[88:91], v65 offset:38912
	s_waitcnt lgkmcnt(0)
	s_barrier
	v_mfma_f32_16x16x32_bf16 v[60:63], v[220:223], v[236:239], v[60:63]
	v_mfma_f32_16x16x32_bf16 v[68:71], v[220:223], v[240:243], v[68:71]
	s_add_u32 m0, s4, 0x8000
	s_nop 0
	global_load_lds_dwordx4 v56, s[0:1]
	v_mfma_f32_16x16x32_bf16 v[52:55], v[220:223], v[244:247], v[52:55]
	v_mfma_f32_16x16x32_bf16 v[40:43], v[220:223], v[248:251], v[40:43]
	s_add_u32 m0, s4, 0x9000
	s_nop 0
	global_load_lds_dwordx4 v57, s[0:1]
	v_mfma_f32_16x16x32_bf16 v[72:75], v[224:227], v[236:239], v[72:75]
	v_mfma_f32_16x16x32_bf16 v[48:51], v[224:227], v[240:243], v[48:51]
	s_add_u32 m0, s4, 0xa000
	s_nop 0
	global_load_lds_dwordx4 v58, s[0:1]
	v_mfma_f32_16x16x32_bf16 v[44:47], v[224:227], v[244:247], v[44:47]
	v_mfma_f32_16x16x32_bf16 v[36:39], v[224:227], v[248:251], v[36:39]
	s_add_u32 m0, s4, 0xb000
	s_nop 0
	global_load_lds_dwordx4 v59, s[0:1]
	v_mfma_f32_16x16x32_bf16 v[32:35], v[228:231], v[236:239], v[32:35]
	v_mfma_f32_16x16x32_bf16 v[28:31], v[228:231], v[240:243], v[28:31]
	s_add_u32 m0, s4, 0xc000
	s_nop 0
	global_load_lds_dwordx4 v56, s[2:3]
	v_mfma_f32_16x16x32_bf16 v[24:27], v[228:231], v[244:247], v[24:27]
	v_mfma_f32_16x16x32_bf16 v[20:23], v[228:231], v[248:251], v[20:23]
	s_add_u32 m0, s4, 0xd000
	s_nop 0
	global_load_lds_dwordx4 v57, s[2:3]
	v_mfma_f32_16x16x32_bf16 v[16:19], v[232:235], v[236:239], v[16:19]
	v_mfma_f32_16x16x32_bf16 v[12:15], v[232:235], v[240:243], v[12:15]
	s_add_u32 m0, s4, 0xe000
	s_nop 0
	global_load_lds_dwordx4 v58, s[2:3]
	v_mfma_f32_16x16x32_bf16 v[8:11], v[232:235], v[244:247], v[8:11]
	v_mfma_f32_16x16x32_bf16 v[4:7], v[232:235], v[248:251], v[4:7]
	s_add_u32 m0, s4, 0xf000
	s_nop 0
	global_load_lds_dwordx4 v59, s[2:3]
	v_mfma_f32_16x16x32_bf16 v[60:63], v[112:115], v[76:79], v[60:63]
	v_mfma_f32_16x16x32_bf16 v[68:71], v[112:115], v[80:83], v[68:71]
	v_mfma_f32_16x16x32_bf16 v[52:55], v[112:115], v[84:87], v[52:55]
	v_mfma_f32_16x16x32_bf16 v[40:43], v[112:115], v[88:91], v[40:43]
	v_mfma_f32_16x16x32_bf16 v[72:75], v[116:119], v[76:79], v[72:75]
	v_mfma_f32_16x16x32_bf16 v[48:51], v[116:119], v[80:83], v[48:51]
	v_mfma_f32_16x16x32_bf16 v[44:47], v[116:119], v[84:87], v[44:47]
	v_mfma_f32_16x16x32_bf16 v[36:39], v[116:119], v[88:91], v[36:39]
	s_add_u32 s0, s0, 0x80
	s_addc_u32 s1, s1, 0
	s_add_u32 s2, s2, 0x80
	s_addc_u32 s3, s3, 0
	s_waitcnt vmcnt(8)
	s_barrier
	v_mfma_f32_16x16x32_bf16 v[32:35], v[120:123], v[76:79], v[32:35]
	ds_read_b128 v[140:143], v66 offset:0
	ds_read_b128 v[144:147], v66 offset:2048
	v_mfma_f32_16x16x32_bf16 v[28:31], v[120:123], v[80:83], v[28:31]
	ds_read_b128 v[148:151], v66 offset:4096
	ds_read_b128 v[152:155], v66 offset:6144
	v_mfma_f32_16x16x32_bf16 v[24:27], v[120:123], v[84:87], v[24:27]
	ds_read_b128 v[156:159], v64 offset:0
	ds_read_b128 v[160:163], v64 offset:2048
	v_mfma_f32_16x16x32_bf16 v[20:23], v[120:123], v[88:91], v[20:23]
	ds_read_b128 v[164:167], v64 offset:4096
	ds_read_b128 v[168:171], v64 offset:6144
	v_mfma_f32_16x16x32_bf16 v[16:19], v[124:127], v[76:79], v[16:19]
	ds_read_b128 v[172:175], v67 offset:0
	ds_read_b128 v[176:179], v67 offset:2048
	v_mfma_f32_16x16x32_bf16 v[12:15], v[124:127], v[80:83], v[12:15]
	ds_read_b128 v[180:183], v67 offset:4096
	ds_read_b128 v[184:187], v67 offset:6144
	v_mfma_f32_16x16x32_bf16 v[8:11], v[124:127], v[84:87], v[8:11]
	ds_read_b128 v[188:191], v65 offset:0
	ds_read_b128 v[192:195], v65 offset:2048
	v_mfma_f32_16x16x32_bf16 v[4:7], v[124:127], v[88:91], v[4:7]
	ds_read_b128 v[196:199], v65 offset:4096
	ds_read_b128 v[200:203], v65 offset:6144
	s_waitcnt lgkmcnt(0)
	s_barrier
	v_mfma_f32_16x16x32_bf16 v[60:63], v[140:143], v[156:159], v[60:63]
	v_mfma_f32_16x16x32_bf16 v[68:71], v[140:143], v[160:163], v[68:71]
	s_add_u32 m0, s4, 0x0
	s_nop 0
	global_load_lds_dwordx4 v56, s[0:1]
	v_mfma_f32_16x16x32_bf16 v[52:55], v[140:143], v[164:167], v[52:55]
	v_mfma_f32_16x16x32_bf16 v[40:43], v[140:143], v[168:171], v[40:43]
	s_add_u32 m0, s4, 0x1000
	s_nop 0
	global_load_lds_dwordx4 v57, s[0:1]
	v_mfma_f32_16x16x32_bf16 v[72:75], v[144:147], v[156:159], v[72:75]
	v_mfma_f32_16x16x32_bf16 v[48:51], v[144:147], v[160:163], v[48:51]
	s_add_u32 m0, s4, 0x2000
	s_nop 0
	global_load_lds_dwordx4 v58, s[0:1]
	v_mfma_f32_16x16x32_bf16 v[44:47], v[144:147], v[164:167], v[44:47]
	v_mfma_f32_16x16x32_bf16 v[36:39], v[144:147], v[168:171], v[36:39]
	s_add_u32 m0, s4, 0x3000
	s_nop 0
	global_load_lds_dwordx4 v59, s[0:1]
	v_mfma_f32_16x16x32_bf16 v[32:35], v[148:151], v[156:159], v[32:35]
	v_mfma_f32_16x16x32_bf16 v[28:31], v[148:151], v[160:163], v[28:31]
	s_add_u32 m0, s4, 0x4000
	s_nop 0
	global_load_lds_dwordx4 v56, s[2:3]
	v_mfma_f32_16x16x32_bf16 v[24:27], v[148:151], v[164:167], v[24:27]
	v_mfma_f32_16x16x32_bf16 v[20:23], v[148:151], v[168:171], v[20:23]
	s_add_u32 m0, s4, 0x5000
	s_nop 0
	global_load_lds_dwordx4 v57, s[2:3]
	v_mfma_f32_16x16x32_bf16 v[16:19], v[152:155], v[156:159], v[16:19]
	v_mfma_f32_16x16x32_bf16 v[12:15], v[152:155], v[160:163], v[12:15]
	s_add_u32 m0, s4, 0x6000
	s_nop 0
	global_load_lds_dwordx4 v58, s[2:3]
	v_mfma_f32_16x16x32_bf16 v[8:11], v[152:155], v[164:167], v[8:11]
	v_mfma_f32_16x16x32_bf16 v[4:7], v[152:155], v[168:171], v[4:7]
	s_add_u32 m0, s4, 0x7000
	s_nop 0
	global_load_lds_dwordx4 v59, s[2:3]
	v_mfma_f32_16x16x32_bf16 v[60:63], v[172:175], v[188:191], v[60:63]
	v_mfma_f32_16x16x32_bf16 v[68:71], v[172:175], v[192:195], v[68:71]
	v_mfma_f32_16x16x32_bf16 v[52:55], v[172:175], v[196:199], v[52:55]
	v_mfma_f32_16x16x32_bf16 v[40:43], v[172:175], v[200:203], v[40:43]
	v_mfma_f32_16x16x32_bf16 v[72:75], v[176:179], v[188:191], v[72:75]
	v_mfma_f32_16x16x32_bf16 v[48:51], v[176:179], v[192:195], v[48:51]
	v_mfma_f32_16x16x32_bf16 v[44:47], v[176:179], v[196:199], v[44:47]
	v_mfma_f32_16x16x32_bf16 v[36:39], v[176:179], v[200:203], v[36:39]
	s_add_u32 s0, s0, 0x80
	s_addc_u32 s1, s1, 0
	s_add_u32 s2, s2, 0x80
	s_addc_u32 s3, s3, 0
	s_waitcnt vmcnt(8)
	s_barrier
	v_mfma_f32_16x16x32_bf16 v[32:35], v[180:183], v[188:191], v[32:35]
	ds_read_b128 v[220:223], v66 offset:32768
	ds_read_b128 v[224:227], v66 offset:34816
	v_mfma_f32_16x16x32_bf16 v[28:31], v[180:183], v[192:195], v[28:31]
	ds_read_b128 v[228:231], v66 offset:36864
	ds_read_b128 v[232:235], v66 offset:38912
	v_mfma_f32_16x16x32_bf16 v[24:27], v[180:183], v[196:199], v[24:27]
	ds_read_b128 v[236:239], v64 offset:32768
	ds_read_b128 v[240:243], v64 offset:34816
	v_mfma_f32_16x16x32_bf16 v[20:23], v[180:183], v[200:203], v[20:23]
	ds_read_b128 v[244:247], v64 offset:36864
	ds_read_b128 v[248:251], v64 offset:38912
	v_mfma_f32_16x16x32_bf16 v[16:19], v[184:187], v[188:191], v[16:19]
	ds_read_b128 v[112:115], v67 offset:32768
	ds_read_b128 v[116:119], v67 offset:34816
	v_mfma_f32_16x16x32_bf16 v[12:15], v[184:187], v[192:195], v[12:15]
	ds_read_b128 v[120:123], v67 offset:36864
	ds_read_b128 v[124:127], v67 offset:38912
	v_mfma_f32_16x16x32_bf16 v[8:11], v[184:187], v[196:199], v[8:11]
	ds_read_b128 v[76:79], v65 offset:32768
	ds_read_b128 v[80:83], v65 offset:34816
	v_mfma_f32_16x16x32_bf16 v[4:7], v[184:187], v[200:203], v[4:7]
	ds_read_b128 v[84:87], v65 offset:36864
	ds_read_b128 v[88:91], v65 offset:38912
	s_waitcnt lgkmcnt(0)
	s_barrier
	v_mfma_f32_16x16x32_bf16 v[60:63], v[220:223], v[236:239], v[60:63]
	v_mfma_f32_16x16x32_bf16 v[68:71], v[220:223], v[240:243], v[68:71]
	s_add_u32 m0, s4, 0x8000
	s_nop 0
	global_load_lds_dwordx4 v56, s[0:1]
	v_mfma_f32_16x16x32_bf16 v[52:55], v[220:223], v[244:247], v[52:55]
	v_mfma_f32_16x16x32_bf16 v[40:43], v[220:223], v[248:251], v[40:43]
	s_add_u32 m0, s4, 0x9000
	s_nop 0
	global_load_lds_dwordx4 v57, s[0:1]
	v_mfma_f32_16x16x32_bf16 v[72:75], v[224:227], v[236:239], v[72:75]
	v_mfma_f32_16x16x32_bf16 v[48:51], v[224:227], v[240:243], v[48:51]
	s_add_u32 m0, s4, 0xa000
	s_nop 0
	global_load_lds_dwordx4 v58, s[0:1]
	v_mfma_f32_16x16x32_bf16 v[44:47], v[224:227], v[244:247], v[44:47]
	v_mfma_f32_16x16x32_bf16 v[36:39], v[224:227], v[248:251], v[36:39]
	s_add_u32 m0, s4, 0xb000
	s_nop 0
	global_load_lds_dwordx4 v59, s[0:1]
	v_mfma_f32_16x16x32_bf16 v[32:35], v[228:231], v[236:239], v[32:35]
	v_mfma_f32_16x16x32_bf16 v[28:31], v[228:231], v[240:243], v[28:31]
	s_add_u32 m0, s4, 0xc000
	s_nop 0
	global_load_lds_dwordx4 v56, s[2:3]
	v_mfma_f32_16x16x32_bf16 v[24:27], v[228:231], v[244:247], v[24:27]
	v_mfma_f32_16x16x32_bf16 v[20:23], v[228:231], v[248:251], v[20:23]
	s_add_u32 m0, s4, 0xd000
	s_nop 0
	global_load_lds_dwordx4 v57, s[2:3]
	v_mfma_f32_16x16x32_bf16 v[16:19], v[232:235], v[236:239], v[16:19]
	v_mfma_f32_16x16x32_bf16 v[12:15], v[232:235], v[240:243], v[12:15]
	s_add_u32 m0, s4, 0xe000
	s_nop 0
	global_load_lds_dwordx4 v58, s[2:3]
	v_mfma_f32_16x16x32_bf16 v[8:11], v[232:235], v[244:247], v[8:11]
	v_mfma_f32_16x16x32_bf16 v[4:7], v[232:235], v[248:251], v[4:7]
	s_add_u32 m0, s4, 0xf000
	s_nop 0
	global_load_lds_dwordx4 v59, s[2:3]
	v_mfma_f32_16x16x32_bf16 v[60:63], v[112:115], v[76:79], v[60:63]
	v_mfma_f32_16x16x32_bf16 v[68:71], v[112:115], v[80:83], v[68:71]
	v_mfma_f32_16x16x32_bf16 v[52:55], v[112:115], v[84:87], v[52:55]
	v_mfma_f32_16x16x32_bf16 v[40:43], v[112:115], v[88:91], v[40:43]
	v_mfma_f32_16x16x32_bf16 v[72:75], v[116:119], v[76:79], v[72:75]
	v_mfma_f32_16x16x32_bf16 v[48:51], v[116:119], v[80:83], v[48:51]
	v_mfma_f32_16x16x32_bf16 v[44:47], v[116:119], v[84:87], v[44:47]
	v_mfma_f32_16x16x32_bf16 v[36:39], v[116:119], v[88:91], v[36:39]
	s_add_u32 s0, s0, 0x80
	s_addc_u32 s1, s1, 0
	s_add_u32 s2, s2, 0x80
	s_addc_u32 s3, s3, 0
	s_waitcnt vmcnt(8)
	s_barrier
	v_mfma_f32_16x16x32_bf16 v[32:35], v[120:123], v[76:79], v[32:35]
	ds_read_b128 v[140:143], v66 offset:0
	ds_read_b128 v[144:147], v66 offset:2048
	v_mfma_f32_16x16x32_bf16 v[28:31], v[120:123], v[80:83], v[28:31]
	ds_read_b128 v[148:151], v66 offset:4096
	ds_read_b128 v[152:155], v66 offset:6144
	v_mfma_f32_16x16x32_bf16 v[24:27], v[120:123], v[84:87], v[24:27]
	ds_read_b128 v[156:159], v64 offset:0
	ds_read_b128 v[160:163], v64 offset:2048
	v_mfma_f32_16x16x32_bf16 v[20:23], v[120:123], v[88:91], v[20:23]
	ds_read_b128 v[164:167], v64 offset:4096
	ds_read_b128 v[168:171], v64 offset:6144
	v_mfma_f32_16x16x32_bf16 v[16:19], v[124:127], v[76:79], v[16:19]
	ds_read_b128 v[172:175], v67 offset:0
	ds_read_b128 v[176:179], v67 offset:2048
	v_mfma_f32_16x16x32_bf16 v[12:15], v[124:127], v[80:83], v[12:15]
	ds_read_b128 v[180:183], v67 offset:4096
	ds_read_b128 v[184:187], v67 offset:6144
	v_mfma_f32_16x16x32_bf16 v[8:11], v[124:127], v[84:87], v[8:11]
	ds_read_b128 v[188:191], v65 offset:0
	ds_read_b128 v[192:195], v65 offset:2048
	v_mfma_f32_16x16x32_bf16 v[4:7], v[124:127], v[88:91], v[4:7]
	ds_read_b128 v[196:199], v65 offset:4096
	ds_read_b128 v[200:203], v65 offset:6144
	s_waitcnt lgkmcnt(0)
	s_barrier
	v_mfma_f32_16x16x32_bf16 v[60:63], v[140:143], v[156:159], v[60:63]
	v_mfma_f32_16x16x32_bf16 v[68:71], v[140:143], v[160:163], v[68:71]
	s_add_u32 m0, s4, 0x0
	s_nop 0
	global_load_lds_dwordx4 v56, s[0:1]
	v_mfma_f32_16x16x32_bf16 v[52:55], v[140:143], v[164:167], v[52:55]
	v_mfma_f32_16x16x32_bf16 v[40:43], v[140:143], v[168:171], v[40:43]
	s_add_u32 m0, s4, 0x1000
	s_nop 0
	global_load_lds_dwordx4 v57, s[0:1]
	v_mfma_f32_16x16x32_bf16 v[72:75], v[144:147], v[156:159], v[72:75]
	v_mfma_f32_16x16x32_bf16 v[48:51], v[144:147], v[160:163], v[48:51]
	s_add_u32 m0, s4, 0x2000
	s_nop 0
	global_load_lds_dwordx4 v58, s[0:1]
	v_mfma_f32_16x16x32_bf16 v[44:47], v[144:147], v[164:167], v[44:47]
	v_mfma_f32_16x16x32_bf16 v[36:39], v[144:147], v[168:171], v[36:39]
	s_add_u32 m0, s4, 0x3000
	s_nop 0
	global_load_lds_dwordx4 v59, s[0:1]
	v_mfma_f32_16x16x32_bf16 v[32:35], v[148:151], v[156:159], v[32:35]
	v_mfma_f32_16x16x32_bf16 v[28:31], v[148:151], v[160:163], v[28:31]
	s_add_u32 m0, s4, 0x4000
	s_nop 0
	global_load_lds_dwordx4 v56, s[2:3]
	v_mfma_f32_16x16x32_bf16 v[24:27], v[148:151], v[164:167], v[24:27]
	v_mfma_f32_16x16x32_bf16 v[20:23], v[148:151], v[168:171], v[20:23]
	s_add_u32 m0, s4, 0x5000
	s_nop 0
	global_load_lds_dwordx4 v57, s[2:3]
	v_mfma_f32_16x16x32_bf16 v[16:19], v[152:155], v[156:159], v[16:19]
	v_mfma_f32_16x16x32_bf16 v[12:15], v[152:155], v[160:163], v[12:15]
	s_add_u32 m0, s4, 0x6000
	s_nop 0
	global_load_lds_dwordx4 v58, s[2:3]
	v_mfma_f32_16x16x32_bf16 v[8:11], v[152:155], v[164:167], v[8:11]
	v_mfma_f32_16x16x32_bf16 v[4:7], v[152:155], v[168:171], v[4:7]
	s_add_u32 m0, s4, 0x7000
	s_nop 0
	global_load_lds_dwordx4 v59, s[2:3]
	v_mfma_f32_16x16x32_bf16 v[60:63], v[172:175], v[188:191], v[60:63]
	v_mfma_f32_16x16x32_bf16 v[68:71], v[172:175], v[192:195], v[68:71]
	v_mfma_f32_16x16x32_bf16 v[52:55], v[172:175], v[196:199], v[52:55]
	v_mfma_f32_16x16x32_bf16 v[40:43], v[172:175], v[200:203], v[40:43]
	v_mfma_f32_16x16x32_bf16 v[72:75], v[176:179], v[188:191], v[72:75]
	v_mfma_f32_16x16x32_bf16 v[48:51], v[176:179], v[192:195], v[48:51]
	v_mfma_f32_16x16x32_bf16 v[44:47], v[176:179], v[196:199], v[44:47]
	v_mfma_f32_16x16x32_bf16 v[36:39], v[176:179], v[200:203], v[36:39]
	s_add_u32 s0, s0, 0x80
	s_addc_u32 s1, s1, 0
	s_add_u32 s2, s2, 0x80
	s_addc_u32 s3, s3, 0
	s_waitcnt vmcnt(8)
	s_barrier
	v_mfma_f32_16x16x32_bf16 v[32:35], v[180:183], v[188:191], v[32:35]
	ds_read_b128 v[220:223], v66 offset:32768
	ds_read_b128 v[224:227], v66 offset:34816
	v_mfma_f32_16x16x32_bf16 v[28:31], v[180:183], v[192:195], v[28:31]
	ds_read_b128 v[228:231], v66 offset:36864
	ds_read_b128 v[232:235], v66 offset:38912
	v_mfma_f32_16x16x32_bf16 v[24:27], v[180:183], v[196:199], v[24:27]
	ds_read_b128 v[236:239], v64 offset:32768
	ds_read_b128 v[240:243], v64 offset:34816
	v_mfma_f32_16x16x32_bf16 v[20:23], v[180:183], v[200:203], v[20:23]
	ds_read_b128 v[244:247], v64 offset:36864
	ds_read_b128 v[248:251], v64 offset:38912
	v_mfma_f32_16x16x32_bf16 v[16:19], v[184:187], v[188:191], v[16:19]
	ds_read_b128 v[112:115], v67 offset:32768
	ds_read_b128 v[116:119], v67 offset:34816
	v_mfma_f32_16x16x32_bf16 v[12:15], v[184:187], v[192:195], v[12:15]
	ds_read_b128 v[120:123], v67 offset:36864
	ds_read_b128 v[124:127], v67 offset:38912
	v_mfma_f32_16x16x32_bf16 v[8:11], v[184:187], v[196:199], v[8:11]
	ds_read_b128 v[76:79], v65 offset:32768
	ds_read_b128 v[80:83], v65 offset:34816
	v_mfma_f32_16x16x32_bf16 v[4:7], v[184:187], v[200:203], v[4:7]
	ds_read_b128 v[84:87], v65 offset:36864
	ds_read_b128 v[88:91], v65 offset:38912
	s_waitcnt lgkmcnt(0)
	s_barrier
	v_mfma_f32_16x16x32_bf16 v[60:63], v[220:223], v[236:239], v[60:63]
	v_mfma_f32_16x16x32_bf16 v[68:71], v[220:223], v[240:243], v[68:71]
	s_add_u32 m0, s4, 0x8000
	s_nop 0
	global_load_lds_dwordx4 v56, s[0:1]
	v_mfma_f32_16x16x32_bf16 v[52:55], v[220:223], v[244:247], v[52:55]
	v_mfma_f32_16x16x32_bf16 v[40:43], v[220:223], v[248:251], v[40:43]
	s_add_u32 m0, s4, 0x9000
	s_nop 0
	global_load_lds_dwordx4 v57, s[0:1]
	v_mfma_f32_16x16x32_bf16 v[72:75], v[224:227], v[236:239], v[72:75]
	v_mfma_f32_16x16x32_bf16 v[48:51], v[224:227], v[240:243], v[48:51]
	s_add_u32 m0, s4, 0xa000
	s_nop 0
	global_load_lds_dwordx4 v58, s[0:1]
	v_mfma_f32_16x16x32_bf16 v[44:47], v[224:227], v[244:247], v[44:47]
	v_mfma_f32_16x16x32_bf16 v[36:39], v[224:227], v[248:251], v[36:39]
	s_add_u32 m0, s4, 0xb000
	s_nop 0
	global_load_lds_dwordx4 v59, s[0:1]
	v_mfma_f32_16x16x32_bf16 v[32:35], v[228:231], v[236:239], v[32:35]
	v_mfma_f32_16x16x32_bf16 v[28:31], v[228:231], v[240:243], v[28:31]
	s_add_u32 m0, s4, 0xc000
	s_nop 0
	global_load_lds_dwordx4 v56, s[2:3]
	v_mfma_f32_16x16x32_bf16 v[24:27], v[228:231], v[244:247], v[24:27]
	v_mfma_f32_16x16x32_bf16 v[20:23], v[228:231], v[248:251], v[20:23]
	s_add_u32 m0, s4, 0xd000
	s_nop 0
	global_load_lds_dwordx4 v57, s[2:3]
	v_mfma_f32_16x16x32_bf16 v[16:19], v[232:235], v[236:239], v[16:19]
	v_mfma_f32_16x16x32_bf16 v[12:15], v[232:235], v[240:243], v[12:15]
	s_add_u32 m0, s4, 0xe000
	s_nop 0
	global_load_lds_dwordx4 v58, s[2:3]
	v_mfma_f32_16x16x32_bf16 v[8:11], v[232:235], v[244:247], v[8:11]
	v_mfma_f32_16x16x32_bf16 v[4:7], v[232:235], v[248:251], v[4:7]
	s_add_u32 m0, s4, 0xf000
	s_nop 0
	global_load_lds_dwordx4 v59, s[2:3]
	v_mfma_f32_16x16x32_bf16 v[60:63], v[112:115], v[76:79], v[60:63]
	v_mfma_f32_16x16x32_bf16 v[68:71], v[112:115], v[80:83], v[68:71]
	v_mfma_f32_16x16x32_bf16 v[52:55], v[112:115], v[84:87], v[52:55]
	v_mfma_f32_16x16x32_bf16 v[40:43], v[112:115], v[88:91], v[40:43]
	v_mfma_f32_16x16x32_bf16 v[72:75], v[116:119], v[76:79], v[72:75]
	v_mfma_f32_16x16x32_bf16 v[48:51], v[116:119], v[80:83], v[48:51]
	v_mfma_f32_16x16x32_bf16 v[44:47], v[116:119], v[84:87], v[44:47]
	v_mfma_f32_16x16x32_bf16 v[36:39], v[116:119], v[88:91], v[36:39]
	s_add_u32 s0, s0, 0x80
	s_addc_u32 s1, s1, 0
	s_add_u32 s2, s2, 0x80
	s_addc_u32 s3, s3, 0
	s_waitcnt vmcnt(8)
	s_barrier
	v_mfma_f32_16x16x32_bf16 v[32:35], v[120:123], v[76:79], v[32:35]
	ds_read_b128 v[140:143], v66 offset:0
	ds_read_b128 v[144:147], v66 offset:2048
	v_mfma_f32_16x16x32_bf16 v[28:31], v[120:123], v[80:83], v[28:31]
	ds_read_b128 v[148:151], v66 offset:4096
	ds_read_b128 v[152:155], v66 offset:6144
	v_mfma_f32_16x16x32_bf16 v[24:27], v[120:123], v[84:87], v[24:27]
	ds_read_b128 v[156:159], v64 offset:0
	ds_read_b128 v[160:163], v64 offset:2048
	v_mfma_f32_16x16x32_bf16 v[20:23], v[120:123], v[88:91], v[20:23]
	ds_read_b128 v[164:167], v64 offset:4096
	ds_read_b128 v[168:171], v64 offset:6144
	v_mfma_f32_16x16x32_bf16 v[16:19], v[124:127], v[76:79], v[16:19]
	ds_read_b128 v[172:175], v67 offset:0
	ds_read_b128 v[176:179], v67 offset:2048
	v_mfma_f32_16x16x32_bf16 v[12:15], v[124:127], v[80:83], v[12:15]
	ds_read_b128 v[180:183], v67 offset:4096
	ds_read_b128 v[184:187], v67 offset:6144
	v_mfma_f32_16x16x32_bf16 v[8:11], v[124:127], v[84:87], v[8:11]
	ds_read_b128 v[188:191], v65 offset:0
	ds_read_b128 v[192:195], v65 offset:2048
	v_mfma_f32_16x16x32_bf16 v[4:7], v[124:127], v[88:91], v[4:7]
	ds_read_b128 v[196:199], v65 offset:4096
	ds_read_b128 v[200:203], v65 offset:6144
	s_waitcnt lgkmcnt(0)
	s_barrier
	v_mfma_f32_16x16x32_bf16 v[60:63], v[140:143], v[156:159], v[60:63]
	v_mfma_f32_16x16x32_bf16 v[68:71], v[140:143], v[160:163], v[68:71]
	v_mfma_f32_16x16x32_bf16 v[52:55], v[140:143], v[164:167], v[52:55]
	v_mfma_f32_16x16x32_bf16 v[40:43], v[140:143], v[168:171], v[40:43]
	v_mfma_f32_16x16x32_bf16 v[72:75], v[144:147], v[156:159], v[72:75]
	v_mfma_f32_16x16x32_bf16 v[48:51], v[144:147], v[160:163], v[48:51]
	v_mfma_f32_16x16x32_bf16 v[44:47], v[144:147], v[164:167], v[44:47]
	v_mfma_f32_16x16x32_bf16 v[36:39], v[144:147], v[168:171], v[36:39]
	v_mfma_f32_16x16x32_bf16 v[32:35], v[148:151], v[156:159], v[32:35]
	v_mfma_f32_16x16x32_bf16 v[28:31], v[148:151], v[160:163], v[28:31]
	v_mfma_f32_16x16x32_bf16 v[24:27], v[148:151], v[164:167], v[24:27]
	v_mfma_f32_16x16x32_bf16 v[20:23], v[148:151], v[168:171], v[20:23]
	v_mfma_f32_16x16x32_bf16 v[16:19], v[152:155], v[156:159], v[16:19]
	v_mfma_f32_16x16x32_bf16 v[12:15], v[152:155], v[160:163], v[12:15]
	v_mfma_f32_16x16x32_bf16 v[8:11], v[152:155], v[164:167], v[8:11]
	v_mfma_f32_16x16x32_bf16 v[4:7], v[152:155], v[168:171], v[4:7]
	v_mfma_f32_16x16x32_bf16 v[60:63], v[172:175], v[188:191], v[60:63]
	v_mfma_f32_16x16x32_bf16 v[68:71], v[172:175], v[192:195], v[68:71]
	v_mfma_f32_16x16x32_bf16 v[52:55], v[172:175], v[196:199], v[52:55]
	v_mfma_f32_16x16x32_bf16 v[40:43], v[172:175], v[200:203], v[40:43]
	v_mfma_f32_16x16x32_bf16 v[72:75], v[176:179], v[188:191], v[72:75]
	v_mfma_f32_16x16x32_bf16 v[48:51], v[176:179], v[192:195], v[48:51]
	v_mfma_f32_16x16x32_bf16 v[44:47], v[176:179], v[196:199], v[44:47]
	v_mfma_f32_16x16x32_bf16 v[36:39], v[176:179], v[200:203], v[36:39]
	s_waitcnt vmcnt(0)
	s_barrier
	v_mfma_f32_16x16x32_bf16 v[32:35], v[180:183], v[188:191], v[32:35]
	ds_read_b128 v[220:223], v66 offset:32768
	ds_read_b128 v[224:227], v66 offset:34816
	v_mfma_f32_16x16x32_bf16 v[28:31], v[180:183], v[192:195], v[28:31]
	ds_read_b128 v[228:231], v66 offset:36864
	ds_read_b128 v[232:235], v66 offset:38912
	v_mfma_f32_16x16x32_bf16 v[24:27], v[180:183], v[196:199], v[24:27]
	ds_read_b128 v[236:239], v64 offset:32768
	ds_read_b128 v[240:243], v64 offset:34816
	v_mfma_f32_16x16x32_bf16 v[20:23], v[180:183], v[200:203], v[20:23]
	ds_read_b128 v[244:247], v64 offset:36864
	ds_read_b128 v[248:251], v64 offset:38912
	v_mfma_f32_16x16x32_bf16 v[16:19], v[184:187], v[188:191], v[16:19]
	ds_read_b128 v[112:115], v67 offset:32768
	ds_read_b128 v[116:119], v67 offset:34816
	v_mfma_f32_16x16x32_bf16 v[12:15], v[184:187], v[192:195], v[12:15]
	ds_read_b128 v[120:123], v67 offset:36864
	ds_read_b128 v[124:127], v67 offset:38912
	v_mfma_f32_16x16x32_bf16 v[8:11], v[184:187], v[196:199], v[8:11]
	ds_read_b128 v[76:79], v65 offset:32768
	ds_read_b128 v[80:83], v65 offset:34816
	v_mfma_f32_16x16x32_bf16 v[4:7], v[184:187], v[200:203], v[4:7]
	ds_read_b128 v[84:87], v65 offset:36864
	ds_read_b128 v[88:91], v65 offset:38912
	s_waitcnt lgkmcnt(0)
	s_barrier
	v_mfma_f32_16x16x32_bf16 v[60:63], v[220:223], v[236:239], v[60:63]
	v_mfma_f32_16x16x32_bf16 v[68:71], v[220:223], v[240:243], v[68:71]
	v_mfma_f32_16x16x32_bf16 v[52:55], v[220:223], v[244:247], v[52:55]
	v_mfma_f32_16x16x32_bf16 v[40:43], v[220:223], v[248:251], v[40:43]
	v_mfma_f32_16x16x32_bf16 v[72:75], v[224:227], v[236:239], v[72:75]
	v_mfma_f32_16x16x32_bf16 v[48:51], v[224:227], v[240:243], v[48:51]
	v_mfma_f32_16x16x32_bf16 v[44:47], v[224:227], v[244:247], v[44:47]
	v_mfma_f32_16x16x32_bf16 v[36:39], v[224:227], v[248:251], v[36:39]
	v_mfma_f32_16x16x32_bf16 v[32:35], v[228:231], v[236:239], v[32:35]
	v_mfma_f32_16x16x32_bf16 v[28:31], v[228:231], v[240:243], v[28:31]
	v_mfma_f32_16x16x32_bf16 v[24:27], v[228:231], v[244:247], v[24:27]
	v_mfma_f32_16x16x32_bf16 v[20:23], v[228:231], v[248:251], v[20:23]
	v_mfma_f32_16x16x32_bf16 v[16:19], v[232:235], v[236:239], v[16:19]
	v_mfma_f32_16x16x32_bf16 v[12:15], v[232:235], v[240:243], v[12:15]
	v_mfma_f32_16x16x32_bf16 v[8:11], v[232:235], v[244:247], v[8:11]
	v_mfma_f32_16x16x32_bf16 v[4:7], v[232:235], v[248:251], v[4:7]
	v_mfma_f32_16x16x32_bf16 v[60:63], v[112:115], v[76:79], v[60:63]
	v_mfma_f32_16x16x32_bf16 v[68:71], v[112:115], v[80:83], v[68:71]
	v_mfma_f32_16x16x32_bf16 v[52:55], v[112:115], v[84:87], v[52:55]
	v_mfma_f32_16x16x32_bf16 v[40:43], v[112:115], v[88:91], v[40:43]
	v_mfma_f32_16x16x32_bf16 v[72:75], v[116:119], v[76:79], v[72:75]
	v_mfma_f32_16x16x32_bf16 v[48:51], v[116:119], v[80:83], v[48:51]
	v_mfma_f32_16x16x32_bf16 v[44:47], v[116:119], v[84:87], v[44:47]
	v_mfma_f32_16x16x32_bf16 v[36:39], v[116:119], v[88:91], v[36:39]
	v_mfma_f32_16x16x32_bf16 v[32:35], v[120:123], v[76:79], v[32:35]
	v_mfma_f32_16x16x32_bf16 v[28:31], v[120:123], v[80:83], v[28:31]
	v_mfma_f32_16x16x32_bf16 v[24:27], v[120:123], v[84:87], v[24:27]
	v_mfma_f32_16x16x32_bf16 v[20:23], v[120:123], v[88:91], v[20:23]
	v_mfma_f32_16x16x32_bf16 v[16:19], v[124:127], v[76:79], v[16:19]
	v_mfma_f32_16x16x32_bf16 v[12:15], v[124:127], v[80:83], v[12:15]
	v_mfma_f32_16x16x32_bf16 v[8:11], v[124:127], v[84:87], v[8:11]
	v_mfma_f32_16x16x32_bf16 v[4:7], v[124:127], v[88:91], v[4:7]
	s_branch .Lg1_join
